# non-temporal (nt) policy on the once-read phase-0 loads (f32 weights and x rows)
# speedup vs baseline: 1.0082x; 1.0082x over previous
.LBB0_20:
	s_cmpk_gt_i32 s90, 0xff
	s_mov_b64 s[0:1], -1
	s_cbranch_scc0 .LBB0_51
	s_cmpk_gt_u32 s90, 0x12ff
	s_cbranch_scc0 .LBB0_25
	v_mov_b32_e32 v0, v194
	s_lshl_b32 s0, s90, 3
	s_add_i32 s0, s0, 0xffff6800
	v_ashrrev_i32_e32 v0, 6, v0
	v_mov_b32_e32 v1, v194
	v_add_u32_e32 v0, s0, v0
	v_readlane_b32 s0, v230, 1
	v_and_b32_e32 v4, 63, v1
	v_ashrrev_i32_e32 v1, 31, v0
	s_waitcnt lgkmcnt(0)
	v_lshlrev_b64 v[2:3], 13, v[0:1]
	v_lshl_add_u64 v[2:3], s[36:37], 0, v[2:3]
	v_lshlrev_b32_e32 v32, 5, v4
	v_lshlrev_b64 v[6:7], 12, v[0:1]
	v_readlane_b32 s1, v230, 2
	v_lshl_add_u64 v[16:17], v[2:3], 0, v[32:33]
	v_cmp_lt_i32_e32 vcc, v60, v59
	v_lshl_add_u64 v[14:15], s[0:1], 0, v[6:7]
	global_load_dwordx4 v[6:9], v[16:17], off offset:16 nt
	global_load_dwordx4 v[10:13], v[16:17], off nt
	v_or_b32_e32 v206, 0x1000, v32
	v_mov_b32_e32 v207, v33
	v_lshl_add_u64 v[204:205], v[2:3], 0, v[206:207]
	global_load_dwordx4 v[232:235], v[16:17], off offset:2064 nt
	global_load_dwordx4 v[236:239], v[16:17], off offset:2048 nt
	global_load_dwordx4 v[240:243], v[204:205], off offset:16 nt
	global_load_dwordx4 v[244:247], v[204:205], off nt
	global_load_dwordx4 v[248:251], v[204:205], off offset:2064 nt
	global_load_dwordx4 v[252:255], v[204:205], off offset:2048 nt
	s_waitcnt vmcnt(6)
	v_mul_f32_e32 v5, v11, v11
	v_fmac_f32_e32 v5, v10, v10
	v_fmac_f32_e32 v5, v12, v12
	v_fmac_f32_e32 v5, v13, v13
	v_fmac_f32_e32 v5, v6, v6
	v_fmac_f32_e32 v5, v7, v7
	v_cvt_pk_bf16_f32 v10, v10, v11
	v_cvt_pk_bf16_f32 v11, v12, v13
	v_cvt_pk_bf16_f32 v12, v6, v7
	v_lshlrev_b32_e32 v6, 4, v4
	v_mov_b32_e32 v7, v33
	v_cvt_pk_bf16_f32 v13, v8, v9
	v_lshl_add_u64 v[14:15], v[14:15], 0, v[6:7]
	v_fmac_f32_e32 v5, v8, v8
	global_store_dwordx4 v[14:15], v[10:13], off
	v_fmac_f32_e32 v5, v9, v9
	s_waitcnt vmcnt(5)
	v_mul_f32_e32 v16, v237, v237
	v_fmac_f32_e32 v16, v236, v236
	v_fmac_f32_e32 v16, v238, v238
	v_fmac_f32_e32 v16, v239, v239
	v_fmac_f32_e32 v16, v232, v232
	v_fmac_f32_e32 v16, v233, v233
	v_cvt_pk_bf16_f32 v10, v236, v237
	v_cvt_pk_bf16_f32 v11, v238, v239
	v_cvt_pk_bf16_f32 v12, v232, v233
	v_cvt_pk_bf16_f32 v13, v234, v235
	v_or_b32_e32 v6, 0x1000, v32
	v_mov_b32_e32 v7, v33
	v_fmac_f32_e32 v16, v234, v234
	global_store_dwordx4 v[14:15], v[10:13], off offset:1024
	v_fmac_f32_e32 v16, v235, v235
	v_add_f32_e32 v5, v5, v16
	v_lshl_add_u64 v[10:11], v[2:3], 0, v[6:7]
	s_nop 0
	v_or_b32_e32 v32, 0x1800, v32
	v_lshl_add_u64 v[2:3], v[2:3], 0, v[32:33]
	s_waitcnt vmcnt(4)
	v_mul_f32_e32 v16, v245, v245
	v_fmac_f32_e32 v16, v244, v244
	v_fmac_f32_e32 v16, v246, v246
	v_fmac_f32_e32 v16, v247, v247
	v_fmac_f32_e32 v16, v240, v240
	v_fmac_f32_e32 v16, v241, v241
	v_cvt_pk_bf16_f32 v10, v244, v245
	v_cvt_pk_bf16_f32 v11, v246, v247
	v_cvt_pk_bf16_f32 v12, v240, v241
	v_cvt_pk_bf16_f32 v13, v242, v243
	v_fmac_f32_e32 v16, v242, v242
	global_store_dwordx4 v[14:15], v[10:13], off offset:2048
	v_fmac_f32_e32 v16, v243, v243
	v_add_f32_e32 v5, v5, v16
	v_cndmask_b32_e32 v3, v58, v60, vcc
	v_lshlrev_b32_e32 v3, 2, v3
	v_cmp_lt_i32_e32 vcc, v61, v59
	s_waitcnt vmcnt(3)
	v_mul_f32_e32 v2, v253, v253
	v_fmac_f32_e32 v2, v252, v252
	v_fmac_f32_e32 v2, v254, v254
	v_fmac_f32_e32 v2, v255, v255
	v_fmac_f32_e32 v2, v248, v248
	v_fmac_f32_e32 v2, v249, v249
	v_fmac_f32_e32 v2, v250, v250
	v_fmac_f32_e32 v2, v251, v251
	v_add_f32_e32 v2, v5, v2
	ds_bpermute_b32 v3, v3, v2
	v_cvt_pk_bf16_f32 v10, v252, v253
	v_cvt_pk_bf16_f32 v11, v254, v255
	v_cvt_pk_bf16_f32 v12, v248, v249
	v_cvt_pk_bf16_f32 v13, v250, v251
	s_waitcnt lgkmcnt(0)
	v_add_f32_e32 v2, v2, v3
	v_cndmask_b32_e32 v3, v58, v61, vcc
	v_lshlrev_b32_e32 v3, 2, v3
	ds_bpermute_b32 v3, v3, v2
	v_cmp_lt_i32_e32 vcc, v62, v59
	global_store_dwordx4 v[14:15], v[10:13], off offset:3072
	s_waitcnt lgkmcnt(0)
	v_add_f32_e32 v2, v2, v3
	v_cndmask_b32_e32 v3, v58, v62, vcc
	v_lshlrev_b32_e32 v3, 2, v3
	ds_bpermute_b32 v3, v3, v2
	v_cmp_lt_i32_e32 vcc, v63, v59
	s_waitcnt lgkmcnt(0)
	v_add_f32_e32 v2, v2, v3
	v_cndmask_b32_e32 v3, v58, v63, vcc
	v_lshlrev_b32_e32 v3, 2, v3
	ds_bpermute_b32 v3, v3, v2
	v_cmp_lt_i32_e32 vcc, v64, v59
	s_waitcnt lgkmcnt(0)
	v_add_f32_e32 v2, v2, v3
	v_cndmask_b32_e32 v3, v58, v64, vcc
	v_lshlrev_b32_e32 v3, 2, v3
	ds_bpermute_b32 v3, v3, v2
	v_cmp_lt_i32_e32 vcc, v65, v59
	s_waitcnt lgkmcnt(0)
	v_add_f32_e32 v2, v2, v3
	v_cndmask_b32_e32 v3, v58, v65, vcc
	v_lshlrev_b32_e32 v3, 2, v3
	ds_bpermute_b32 v3, v3, v2
	v_cmp_eq_u32_e32 vcc, 0, v4
	s_and_saveexec_b64 s[0:1], vcc
	s_cbranch_execz .LBB0_24
	s_waitcnt lgkmcnt(0)
	v_add_f32_e32 v2, v2, v3
	v_fmamk_f32 v2, v2, 0x3a000000, v55
	s_mov_b32 s4, 0x800000
	v_mul_f32_e32 v3, 0x4b800000, v2
	v_cmp_gt_f32_e32 vcc, s4, v2
	s_mov_b32 s3, s31
	v_readlane_b32 s28, v230, 3
	v_cndmask_b32_e32 v2, v2, v3, vcc
	v_rsq_f32_e32 v2, v2
	v_readlane_b32 s29, v230, 4
	v_readlane_b32 s31, v230, 6
	s_mov_b32 s31, s3
	v_mul_f32_e32 v3, 0x45800000, v2
	v_cndmask_b32_e32 v2, v2, v3, vcc
	v_lshl_add_u64 v[0:1], v[0:1], 2, s[28:29]
	v_readlane_b32 s30, v230, 5
	global_store_dword v[0:1], v2, off

.LBB0_25:
	s_andn2_b64 vcc, exec, s[0:1]
	s_cbranch_vccnz .LBB0_50
	s_add_i32 s0, s90, 0xff00
	s_and_b32 s1, s0, 0xffff
	s_mul_i32 s1, s1, 0xe38f
	s_lshr_b32 s5, s1, 26
	s_mul_i32 s1, s5, 0x480
	s_sub_i32 s0, s0, s1
	s_and_b32 s4, s0, 0xffff
	s_cmpk_gt_u32 s4, 0x2ff
	s_mov_b64 s[0:1], -1
	s_cbranch_scc0 .LBB0_32
	s_and_b32 s7, s5, 0xffff
	s_cmpk_gt_u32 s4, 0x37f
	s_cbranch_scc0 .LBB0_29
	v_readlane_b32 s52, v230, 18
	s_lshl_b32 s0, s7, 24
	v_readlane_b32 s58, v230, 24
	v_readlane_b32 s59, v230, 25
	s_add_u32 s10, s58, s0
	v_readlane_b32 s66, v230, 32
	s_addc_u32 s11, s59, 0
	s_lshl_b32 s0, s7, 23
	v_readlane_b32 s67, v230, 33
	s_add_u32 s1, s66, s0
	s_addc_u32 s28, s67, 0
	v_mov_b32_e32 v52, v194
	s_lshl_b32 s29, s4, 3
	s_lshl_b32 s0, s4, 8
	v_lshlrev_b32_e32 v0, 2, v52
	s_and_b32 s29, s29, 0x3fc0
	v_ashrrev_i32_e32 v53, 6, v52
	v_and_b32_e32 v72, 0xfc, v0
	s_and_b32 s0, s0, 0x700
	s_add_i32 s70, s29, 0xffffe400
	v_or_b32_e32 v1, s0, v72
	v_add_u32_e32 v0, s70, v53
	v_lshlrev_b32_e32 v32, 2, v1
	v_ashrrev_i32_e32 v1, 31, v0
	s_waitcnt lgkmcnt(0)
	v_lshl_add_u64 v[2:3], s[10:11], 0, v[32:33]
	v_lshlrev_b64 v[0:1], 13, v[0:1]
	v_lshl_add_u64 v[28:29], v[2:3], 0, v[0:1]
	v_add_co_u32_e32 v4, vcc, s72, v28
	s_nop 1
	v_addc_co_u32_e32 v5, vcc, 0, v29, vcc
	v_add_co_u32_e32 v8, vcc, s73, v28
	s_barrier
	s_nop 0
	v_addc_co_u32_e32 v9, vcc, 0, v29, vcc
	v_add_co_u32_e32 v12, vcc, s74, v28
	s_nop 1
	v_addc_co_u32_e32 v13, vcc, 0, v29, vcc
	v_add_co_u32_e32 v16, vcc, s24, v28
	global_load_dwordx4 v[0:3], v[28:29], off nt
	s_nop 0
	v_addc_co_u32_e32 v17, vcc, 0, v29, vcc
	global_load_dwordx4 v[4:7], v[4:5], off nt
	v_add_co_u32_e32 v20, vcc, s25, v28
	global_load_dwordx4 v[8:11], v[8:9], off nt
	s_nop 0
	v_addc_co_u32_e32 v21, vcc, 0, v29, vcc
	global_load_dwordx4 v[12:15], v[12:13], off nt
	v_add_co_u32_e32 v24, vcc, s26, v28
	global_load_dwordx4 v[16:19], v[16:17], off nt
	s_nop 0
	v_addc_co_u32_e32 v25, vcc, 0, v29, vcc
	global_load_dwordx4 v[20:23], v[20:21], off nt
	v_add_co_u32_e32 v28, vcc, s27, v28
	global_load_dwordx4 v[24:27], v[24:25], off nt
	s_nop 0
	v_addc_co_u32_e32 v29, vcc, 0, v29, vcc
	global_load_dwordx4 v[28:31], v[28:29], off nt
	v_mul_lo_u32 v32, v53, s75
	v_lshl_add_u32 v32, v72, 2, v32
	s_lshl_b64 s[10:11], s[70:71], 1
	s_add_u32 s10, s1, s10
	s_addc_u32 s11, s28, s11
	v_readlane_b32 s53, v230, 19
	v_readlane_b32 s54, v230, 20
	v_readlane_b32 s55, v230, 21
	v_readlane_b32 s56, v230, 22
	v_readlane_b32 s57, v230, 23
	v_readlane_b32 s60, v230, 26
	v_readlane_b32 s61, v230, 27
	v_readlane_b32 s62, v230, 28
	v_readlane_b32 s63, v230, 29
	v_readlane_b32 s64, v230, 30
	v_readlane_b32 s65, v230, 31
	s_brev_b32 s70, 1
	s_waitcnt vmcnt(7)
	ds_write_b128 v32, v[0:3]
	s_waitcnt vmcnt(6)
	ds_write_b128 v32, v[4:7] offset:8320
	s_waitcnt vmcnt(5)
	ds_write_b128 v32, v[8:11] offset:16640
	s_waitcnt vmcnt(4)
	ds_write_b128 v32, v[12:15] offset:24960
	s_waitcnt vmcnt(3)
	ds_write_b128 v32, v[16:19] offset:33280
	s_waitcnt vmcnt(2)
	ds_write_b128 v32, v[20:23] offset:41600
	s_waitcnt vmcnt(1)
	ds_write_b128 v32, v[24:27] offset:49920
	s_waitcnt vmcnt(0)
	ds_write_b128 v32, v[28:31] offset:58240
	v_ashrrev_i32_e32 v0, 3, v52
	v_and_b32_e32 v26, 63, v52
	v_and_b32_e32 v2, -8, v0
	v_ashrrev_i32_e32 v3, 31, v2
	v_lshlrev_b32_e32 v6, 2, v26
	v_or_b32_e32 v5, 7, v0
	v_lshl_add_u64 v[0:1], v[2:3], 1, s[10:11]
	v_mad_u64_u32 v[8:9], s[10:11], v2, s75, v[6:7]
	v_add_u32_e32 v28, 16, v8
	s_waitcnt lgkmcnt(0)
	s_barrier
	ds_read2st64_b32 v[10:11], v8 offset1:1
	ds_read2st64_b32 v[12:13], v28 offset0:4 offset1:5
	v_add_u32_e32 v29, 48, v8
	ds_read2st64_b32 v[16:17], v29 offset0:12 offset1:13
	v_add_u32_e32 v30, 0x50, v8
	ds_read2st64_b32 v[20:21], v30 offset0:20 offset1:21
	s_waitcnt lgkmcnt(2)
	v_cvt_pk_bf16_f32 v2, v10, v12
	v_add_u32_e32 v12, 32, v8
	ds_read2st64_b32 v[14:15], v12 offset0:8 offset1:9
	v_mad_u64_u32 v[6:7], s[10:11], v5, s75, v[6:7]
	ds_read2st64_b32 v[24:25], v6 offset1:1
	v_or_b32_e32 v7, s0, v26
	s_waitcnt lgkmcnt(1)
	v_cvt_pk_bf16_f32 v3, v14, v16
	v_add_u32_e32 v16, 64, v8
	ds_read2st64_b32 v[18:19], v16 offset0:16 offset1:17
	v_lshlrev_b32_e32 v32, 12, v7
	v_lshl_add_u64 v[26:27], v[0:1], 0, v[32:33]
	v_or_b32_e32 v10, 0x40000, v32
	s_mov_b64 s[0:1], 0
	s_waitcnt lgkmcnt(0)
	v_cvt_pk_bf16_f32 v4, v18, v20
	v_add_u32_e32 v20, 0x60, v8
	ds_read2st64_b32 v[22:23], v20 offset0:24 offset1:25
	s_waitcnt lgkmcnt(0)
	v_cvt_pk_bf16_f32 v5, v22, v24
	global_store_dwordx4 v[26:27], v[2:5], off
	v_or_b32_e32 v22, 0x80000, v32
	v_or_b32_e32 v32, 0xc0000, v32
	v_cvt_pk_bf16_f32 v2, v11, v13
	v_mov_b32_e32 v11, v33
	v_cvt_pk_bf16_f32 v3, v15, v17
	v_cvt_pk_bf16_f32 v4, v19, v21
	v_cvt_pk_bf16_f32 v5, v23, v25
	v_lshl_add_u64 v[10:11], v[0:1], 0, v[10:11]
	global_store_dwordx4 v[10:11], v[2:5], off
	ds_read2st64_b32 v[8:9], v8 offset0:2 offset1:3
	ds_read2st64_b32 v[10:11], v28 offset0:6 offset1:7
	ds_read2st64_b32 v[12:13], v12 offset0:10 offset1:11
	ds_read2st64_b32 v[14:15], v29 offset0:14 offset1:15
	ds_read2st64_b32 v[16:17], v16 offset0:18 offset1:19
	ds_read2st64_b32 v[18:19], v30 offset0:22 offset1:23
	ds_read2st64_b32 v[20:21], v20 offset0:26 offset1:27
	ds_read2st64_b32 v[6:7], v6 offset0:2 offset1:3
	v_mov_b32_e32 v23, v33
	s_waitcnt lgkmcnt(6)
	v_cvt_pk_bf16_f32 v2, v8, v10
	s_waitcnt lgkmcnt(4)
	v_cvt_pk_bf16_f32 v3, v12, v14
	s_waitcnt lgkmcnt(2)
	v_cvt_pk_bf16_f32 v4, v16, v18
	s_waitcnt lgkmcnt(0)
	v_cvt_pk_bf16_f32 v5, v20, v6
	v_lshl_add_u64 v[22:23], v[0:1], 0, v[22:23]
	global_store_dwordx4 v[22:23], v[2:5], off
	v_lshl_add_u64 v[0:1], v[0:1], 0, v[32:33]
	s_nop 0
	v_cvt_pk_bf16_f32 v2, v9, v11
	v_cvt_pk_bf16_f32 v3, v13, v15
	v_cvt_pk_bf16_f32 v4, v17, v19
	v_cvt_pk_bf16_f32 v5, v21, v7
	global_store_dwordx4 v[0:1], v[2:5], off
.LBB0_29:
	s_andn2_b64 vcc, exec, s[0:1]
	s_cbranch_vccnz .LBB0_31
	v_readlane_b32 s52, v230, 18
	s_lshl_b32 s0, s7, 23
	v_readlane_b32 s56, v230, 22
	v_readlane_b32 s57, v230, 23
	s_add_u32 s10, s56, s0
	v_readlane_b32 s64, v230, 30
	s_addc_u32 s11, s57, 0
	s_lshl_b32 s0, s7, 22
	v_mov_b32_e32 v52, v194
	v_readlane_b32 s65, v230, 31
	s_add_u32 s1, s64, s0
	s_addc_u32 s7, s65, 0
	v_lshlrev_b32_e32 v0, 2, v52
	v_and_b32_e32 v72, 0xfc, v0
	s_lshl_b32 s28, s4, 8
	s_and_b32 s0, s28, 0x700
	v_or_b32_e32 v1, s28, v72
	s_lshl_b32 s28, s4, 3
	v_lshrrev_b32_e32 v1, 1, v1
	v_lshlrev_b32_e32 v2, 7, v52
	s_and_b32 s28, s28, 0x1fc0
	v_ashrrev_i32_e32 v53, 6, v52
	v_and_b32_e32 v1, 0x3e0, v1
	v_and_b32_e32 v0, 28, v0
	v_and_b32_e32 v2, 0x400, v2
	s_add_i32 s70, s28, 0xffffe800
	v_or3_b32 v1, v2, v0, v1
	v_add_u32_e32 v0, s70, v53
	v_lshlrev_b32_e32 v32, 2, v1
	v_ashrrev_i32_e32 v1, 31, v0
	s_waitcnt lgkmcnt(0)
	v_lshl_add_u64 v[2:3], s[10:11], 0, v[32:33]
	v_lshlrev_b64 v[0:1], 13, v[0:1]
	v_lshl_add_u64 v[28:29], v[2:3], 0, v[0:1]
	v_add_co_u32_e32 v4, vcc, s72, v28
	s_nop 1
	v_addc_co_u32_e32 v5, vcc, 0, v29, vcc
	v_add_co_u32_e32 v8, vcc, s73, v28
	s_barrier
	s_nop 0
	v_addc_co_u32_e32 v9, vcc, 0, v29, vcc
	v_add_co_u32_e32 v12, vcc, s74, v28
	s_nop 1
	v_addc_co_u32_e32 v13, vcc, 0, v29, vcc
	v_add_co_u32_e32 v16, vcc, s24, v28
	global_load_dwordx4 v[0:3], v[28:29], off nt
	s_nop 0
	v_addc_co_u32_e32 v17, vcc, 0, v29, vcc
	global_load_dwordx4 v[4:7], v[4:5], off nt
	v_add_co_u32_e32 v20, vcc, s25, v28
	global_load_dwordx4 v[8:11], v[8:9], off nt
	s_nop 0
	v_addc_co_u32_e32 v21, vcc, 0, v29, vcc
	global_load_dwordx4 v[12:15], v[12:13], off nt
	v_add_co_u32_e32 v24, vcc, s26, v28
	global_load_dwordx4 v[16:19], v[16:17], off nt
	s_nop 0
	v_addc_co_u32_e32 v25, vcc, 0, v29, vcc
	global_load_dwordx4 v[20:23], v[20:21], off nt
	v_add_co_u32_e32 v28, vcc, s27, v28
	global_load_dwordx4 v[24:27], v[24:25], off nt
	s_nop 0
	v_addc_co_u32_e32 v29, vcc, 0, v29, vcc
	global_load_dwordx4 v[28:31], v[28:29], off nt
	v_mul_lo_u32 v32, v53, s75
	v_lshl_add_u32 v32, v72, 2, v32
	s_lshl_b64 s[10:11], s[70:71], 1
	s_add_u32 s10, s1, s10
	s_addc_u32 s11, s7, s11
	s_brev_b32 s70, 1
	v_readlane_b32 s53, v230, 19
	v_readlane_b32 s54, v230, 20
	v_readlane_b32 s55, v230, 21
	v_readlane_b32 s58, v230, 24
	v_readlane_b32 s59, v230, 25
	v_readlane_b32 s60, v230, 26
	v_readlane_b32 s61, v230, 27
	v_readlane_b32 s62, v230, 28
	v_readlane_b32 s63, v230, 29
	v_readlane_b32 s66, v230, 32
	v_readlane_b32 s67, v230, 33
	s_waitcnt vmcnt(7)
	ds_write_b128 v32, v[0:3]
	s_waitcnt vmcnt(6)
	ds_write_b128 v32, v[4:7] offset:8320
	s_waitcnt vmcnt(5)
	ds_write_b128 v32, v[8:11] offset:16640
	s_waitcnt vmcnt(4)
	ds_write_b128 v32, v[12:15] offset:24960
	s_waitcnt vmcnt(3)
	ds_write_b128 v32, v[16:19] offset:33280
	s_waitcnt vmcnt(2)
	ds_write_b128 v32, v[20:23] offset:41600
	s_waitcnt vmcnt(1)
	ds_write_b128 v32, v[24:27] offset:49920
	s_waitcnt vmcnt(0)
	ds_write_b128 v32, v[28:31] offset:58240
	v_ashrrev_i32_e32 v0, 3, v52
	v_and_b32_e32 v26, 63, v52
	v_and_b32_e32 v2, -8, v0
	v_ashrrev_i32_e32 v3, 31, v2
	v_lshlrev_b32_e32 v6, 2, v26
	v_or_b32_e32 v5, 7, v0
	v_lshl_add_u64 v[0:1], v[2:3], 1, s[10:11]
	v_mad_u64_u32 v[8:9], s[10:11], v2, s75, v[6:7]
	v_add_u32_e32 v28, 16, v8
	s_waitcnt lgkmcnt(0)
	s_barrier
	ds_read2st64_b32 v[10:11], v8 offset1:1
	ds_read2st64_b32 v[12:13], v28 offset0:4 offset1:5
	v_add_u32_e32 v29, 48, v8
	ds_read2st64_b32 v[16:17], v29 offset0:12 offset1:13
	v_add_u32_e32 v30, 0x50, v8
	ds_read2st64_b32 v[20:21], v30 offset0:20 offset1:21
	s_waitcnt lgkmcnt(2)
	v_cvt_pk_bf16_f32 v2, v10, v12
	v_add_u32_e32 v12, 32, v8
	ds_read2st64_b32 v[14:15], v12 offset0:8 offset1:9
	v_mad_u64_u32 v[6:7], s[10:11], v5, s75, v[6:7]
	ds_read2st64_b32 v[24:25], v6 offset1:1
	v_or_b32_e32 v7, s0, v26
	s_waitcnt lgkmcnt(1)
	v_cvt_pk_bf16_f32 v3, v14, v16
	v_add_u32_e32 v16, 64, v8
	ds_read2st64_b32 v[18:19], v16 offset0:16 offset1:17
	v_lshlrev_b32_e32 v32, 11, v7
	v_lshl_add_u64 v[26:27], v[0:1], 0, v[32:33]
	v_or_b32_e32 v10, 0x20000, v32
	s_waitcnt lgkmcnt(0)
	v_cvt_pk_bf16_f32 v4, v18, v20
	v_add_u32_e32 v20, 0x60, v8
	ds_read2st64_b32 v[22:23], v20 offset0:24 offset1:25
	s_waitcnt lgkmcnt(0)
	v_cvt_pk_bf16_f32 v5, v22, v24
	global_store_dwordx4 v[26:27], v[2:5], off
	v_or_b32_e32 v22, 0x40000, v32
	v_or_b32_e32 v32, 0x60000, v32
	v_cvt_pk_bf16_f32 v2, v11, v13
	v_mov_b32_e32 v11, v33
	v_cvt_pk_bf16_f32 v3, v15, v17
	v_cvt_pk_bf16_f32 v4, v19, v21
	v_cvt_pk_bf16_f32 v5, v23, v25
	v_lshl_add_u64 v[10:11], v[0:1], 0, v[10:11]
	global_store_dwordx4 v[10:11], v[2:5], off
	ds_read2st64_b32 v[8:9], v8 offset0:2 offset1:3
	ds_read2st64_b32 v[10:11], v28 offset0:6 offset1:7
	ds_read2st64_b32 v[12:13], v12 offset0:10 offset1:11
	ds_read2st64_b32 v[14:15], v29 offset0:14 offset1:15
	ds_read2st64_b32 v[16:17], v16 offset0:18 offset1:19
	ds_read2st64_b32 v[18:19], v30 offset0:22 offset1:23
	ds_read2st64_b32 v[20:21], v20 offset0:26 offset1:27
	ds_read2st64_b32 v[6:7], v6 offset0:2 offset1:3
	v_mov_b32_e32 v23, v33
	s_waitcnt lgkmcnt(6)
	v_cvt_pk_bf16_f32 v2, v8, v10
	s_waitcnt lgkmcnt(4)
	v_cvt_pk_bf16_f32 v3, v12, v14
	s_waitcnt lgkmcnt(2)
	v_cvt_pk_bf16_f32 v4, v16, v18
	s_waitcnt lgkmcnt(0)
	v_cvt_pk_bf16_f32 v5, v20, v6
	v_lshl_add_u64 v[22:23], v[0:1], 0, v[22:23]
	global_store_dwordx4 v[22:23], v[2:5], off
	v_lshl_add_u64 v[0:1], v[0:1], 0, v[32:33]
	s_nop 0
	v_cvt_pk_bf16_f32 v2, v9, v11
	v_cvt_pk_bf16_f32 v3, v13, v15
	v_cvt_pk_bf16_f32 v4, v17, v19
	v_cvt_pk_bf16_f32 v5, v21, v7
	global_store_dwordx4 v[0:1], v[2:5], off

.LBB0_32:
	s_andn2_b64 vcc, exec, s[0:1]
	s_cbranch_vccnz .LBB0_50
	s_and_b32 s5, 0xffff, s5
	s_mul_i32 s0, s5, 0x3000000
	s_add_u32 s0, s44, s0
	s_addc_u32 s1, s45, 0
	s_lshl_b32 s7, s5, 13
	s_add_u32 s10, s40, s7
	s_mul_i32 s7, s4, 0xaaab
	s_addc_u32 s11, s41, 0
	s_lshr_b32 s7, s7, 20
	s_mul_i32 s28, s7, 24
	s_sub_i32 s4, s4, s28
	v_mov_b32_e32 v72, v194
	s_lshl_b32 s4, s4, 8
	v_lshlrev_b32_e32 v0, 2, v72
	v_and_b32_e32 v74, 0xfc, v0
	s_and_b32 s4, s4, 0xff00
	s_lshl_b32 s7, s7, 6
	v_ashrrev_i32_e32 v73, 6, v72
	v_or_b32_e32 v0, s4, v74
	s_and_b32 s28, s7, 0xffc0
	v_add_u32_e32 v52, s28, v73
	v_lshlrev_b32_e32 v32, 2, v0
	v_lshl_add_u64 v[0:1], s[0:1], 0, v[32:33]
	v_add_u32_e32 v4, 8, v52
	s_waitcnt lgkmcnt(0)
	v_mad_i64_i32 v[2:3], s[0:1], v52, s33, v[0:1]
	v_mad_i64_i32 v[4:5], s[0:1], v4, s33, v[0:1]
	s_barrier
	global_load_dwordx4 v[28:31], v[2:3], off nt
	global_load_dwordx4 v[24:27], v[4:5], off nt
	v_add_u32_e32 v2, 16, v52
	v_add_u32_e32 v4, 24, v52
	v_mad_i64_i32 v[2:3], s[0:1], v2, s33, v[0:1]
	v_mad_i64_i32 v[4:5], s[0:1], v4, s33, v[0:1]
	global_load_dwordx4 v[20:23], v[2:3], off nt
	global_load_dwordx4 v[16:19], v[4:5], off nt
	v_add_u32_e32 v2, 32, v52
	v_add_u32_e32 v4, 40, v52
	v_mad_i64_i32 v[2:3], s[0:1], v2, s33, v[0:1]
	v_mad_i64_i32 v[4:5], s[0:1], v4, s33, v[0:1]
	global_load_dwordx4 v[12:15], v[2:3], off nt
	global_load_dwordx4 v[8:11], v[4:5], off nt
	v_add_u32_e32 v2, 48, v52
	v_add_u32_e32 v4, 56, v52
	v_mad_i64_i32 v[2:3], s[0:1], v2, s33, v[0:1]
	v_mad_i64_i32 v[0:1], s[0:1], v4, s33, v[0:1]
	global_load_dwordx4 v[4:7], v[2:3], off nt
	s_nop 0
	global_load_dwordx4 v[0:3], v[0:1], off nt
	v_ashrrev_i32_e32 v53, 31, v52
	v_cmp_ne_u32_e64 s[0:1], 1, v56
	s_andn2_b64 vcc, exec, s[68:69]
	v_lshl_add_u64 v[52:53], v[52:53], 2, s[10:11]
	s_cbranch_vccnz .LBB0_35
	global_load_dword v32, v[52:53], off
	s_waitcnt vmcnt(0)
	v_pk_mul_f32 v[28:29], v[28:29], v[32:33] op_sel_hi:[1,0]
	v_pk_mul_f32 v[30:31], v[30:31], v[32:33] op_sel_hi:[1,0]

.LBB0_71:
	s_add_u32 s54, s30, s0
	s_addc_u32 s55, s31, s1
	global_load_dwordx4 v[6:9], v33, s[54:55] offset:16 nt
	global_load_dwordx4 v[10:13], v33, s[54:55] nt
	s_add_u32 s54, s28, s0
	s_addc_u32 s55, s29, s1
	global_load_dwordx4 v[14:17], v33, s[54:55] offset:16 nt
	global_load_dwordx4 v[18:21], v33, s[54:55] nt
	s_add_u32 s54, s10, s0
	s_addc_u32 s55, s11, s1
	global_load_dwordx4 v[22:25], v33, s[54:55] offset:16 nt
	global_load_dwordx4 v[28:31], v33, s[54:55] nt
	s_add_u32 s54, s5, s0
	s_addc_u32 s55, s7, s1
	global_load_dwordx4 v[72:75], v33, s[54:55] offset:16 nt
	global_load_dwordx4 v[76:79], v33, s[54:55] nt
	s_add_u32 s0, s0, 32
	s_addc_u32 s1, s1, 0
	s_cmpk_eq_i32 s0, 0x100
	s_waitcnt vmcnt(6)
	v_mov_b32_e32 v52, v10
	v_mov_b32_e32 v10, v12
	s_waitcnt vmcnt(5)
	v_mov_b32_e32 v12, v14
	s_waitcnt vmcnt(4)
	v_mov_b32_e32 v80, v18
	v_mov_b32_e32 v18, v20
	s_waitcnt vmcnt(2)
	v_mov_b32_e32 v53, v28
	v_mov_b32_e32 v28, v11
	v_mov_b32_e32 v11, v30
	s_waitcnt vmcnt(0)
	v_mov_b32_e32 v81, v76
	v_pk_fma_f32 v[4:5], v[52:53], v[80:81], v[4:5]
	v_mov_b32_e32 v76, v19
	v_pk_fma_f32 v[4:5], v[28:29], v[76:77], v[4:5]
	v_mov_b32_e32 v19, v78
	v_pk_fma_f32 v[4:5], v[10:11], v[18:19], v[4:5]
	v_mov_b32_e32 v30, v13
	v_mov_b32_e32 v78, v21
	v_pk_fma_f32 v[4:5], v[30:31], v[78:79], v[4:5]
	v_mov_b32_e32 v10, v6
	v_mov_b32_e32 v11, v22
	v_mov_b32_e32 v13, v72
	v_pk_fma_f32 v[4:5], v[10:11], v[12:13], v[4:5]
	v_mov_b32_e32 v22, v7
	v_mov_b32_e32 v72, v15
	v_pk_fma_f32 v[4:5], v[22:23], v[72:73], v[4:5]
	v_mov_b32_e32 v6, v8
	v_mov_b32_e32 v7, v24
	v_mov_b32_e32 v10, v16
	v_mov_b32_e32 v11, v74
	v_pk_fma_f32 v[4:5], v[6:7], v[10:11], v[4:5]
	v_mov_b32_e32 v24, v9
	v_mov_b32_e32 v74, v17
	v_pk_fma_f32 v[4:5], v[24:25], v[74:75], v[4:5]
	s_cbranch_scc0 .LBB0_71
	v_cvt_f32_i32_e32 v1, s4
	s_mov_b32 s5, 0x42b17218
	v_readlane_b32 s28, v230, 3
	v_readlane_b32 s30, v230, 5
	v_mul_f32_e32 v1, 0xbe99999a, v1
	v_mul_f32_e32 v6, 0x3fb8aa3b, v1
	v_fma_f32 v7, v1, s99, -v6
	v_rndne_f32_e32 v8, v6
	v_fmac_f32_e32 v7, 0x32a5705f, v1
	v_sub_f32_e32 v6, v6, v8
	v_add_f32_e32 v6, v6, v7
	v_exp_f32_e32 v6, v6
	v_cvt_i32_f32_e32 v7, v8
	v_cmp_ngt_f32_e64 s[0:1], s23, v1
	v_readlane_b32 s31, v230, 6
	v_readlane_b32 s29, v230, 4
	v_ldexp_f32 v6, v6, v7
	v_cndmask_b32_e64 v6, 0, v6, s[0:1]
	v_cmp_nlt_f32_e64 s[0:1], s5, v1
	s_nop 1
	v_cndmask_b32_e64 v1, v70, v6, s[0:1]
	v_mul_f32_e32 v6, 0x3fb8aa3b, v4
	v_rndne_f32_e32 v7, v6
	v_sub_f32_e32 v8, v6, v7
	v_fma_f32 v6, v4, s99, -v6
	v_fmac_f32_e32 v6, 0x32a5705f, v4
	v_add_f32_e32 v6, v8, v6
	v_exp_f32_e32 v6, v6
	v_cvt_i32_f32_e32 v7, v7
	v_cmp_ngt_f32_e64 s[0:1], s23, v4
	v_fmamk_f32 v1, v1, 0xbf19999a, v57
	v_ldexp_f32 v6, v6, v7
	v_cndmask_b32_e64 v6, 0, v6, s[0:1]
	v_cmp_nlt_f32_e64 s[0:1], s5, v4
	s_nop 1
	v_cndmask_b32_e64 v4, v70, v6, s[0:1]
	v_mul_f32_e32 v6, 0x3fb8aa3b, v5
	v_rndne_f32_e32 v7, v6
	v_sub_f32_e32 v8, v6, v7
	v_fma_f32 v6, v5, s99, -v6
	v_fmac_f32_e32 v6, 0x32a5705f, v5
	v_add_f32_e32 v6, v8, v6
	v_exp_f32_e32 v6, v6
	v_cvt_i32_f32_e32 v7, v7
	v_cmp_ngt_f32_e64 s[0:1], s23, v5
	v_ldexp_f32 v6, v6, v7
	s_nop 0
	v_cndmask_b32_e64 v6, 0, v6, s[0:1]
	v_cmp_nlt_f32_e64 s[0:1], s5, v5
	s_ashr_i32 s5, s4, 31
	s_nop 0
	v_cndmask_b32_e64 v5, v70, v6, s[0:1]
	s_lshl_b64 s[0:1], s[4:5], 2
	v_sub_f32_e32 v4, v4, v5
	s_add_u32 s0, s30, s0
	v_add_f32_e32 v1, v1, v4
	s_addc_u32 s1, s31, s1
	s_mov_b32 s31, s9
	global_store_dword v33, v1, s[0:1]
